# P2 main k-loop rescheduled: counted lgkmcnt ladder, unmasked 3-instr LDS-DMA interleaved between MFMAs
# speedup vs baseline: 1.0419x; 1.0115x over previous
; DI int tid_() { int t = threadIdx.x; asm volatile("" : "+v"(t)); return t; }
; DI void wait_vm0() { asm volatile("s_waitcnt vmcnt(0)" ::: "memory"); }
; DI void bar_() { __builtin_amdgcn_s_barrier(); }
; template <int TM, int TN, int WM, int WN, bool SUMSQ, int NST, class AF, class BF, class AFN, class BFN>
; DI void gemm8x(f32x16 (&acc)[TM][TN], AF arow, BF brow, int K, char* smem, float& sumsq, bool pre, bool hasNext, AFN arowN, BFN browN) {
;     ...
;   const int t = tid_(), lane = t & 63, w = t >> 6, r = lane & 31, hh = lane >> 5;
;   const int wm = w % WM, wn = w / WM;
;   const int row0 = t >> 3;
;   const int c = (t & 7) ^ ((row0 >> 1) & 7);
;   const bool a0v = row0 < RA, a1v = row0 + 64 < RA, a2v = row0 + 128 < RA, a3v = row0 + 192 < RA;
;   const bool b0v = row0 < RB, b1v = row0 + 64 < RB, b2v = row0 + 128 < RB, b3v = row0 + 192 < RB;
;   const bf16_t* pa0 = arow(a0v ? row0 : 0) + c * 8;
;   const bf16_t* pa1 = arow(a1v ? row0 + 64 : 0) + c * 8;
;   const bf16_t* pa2 = arow(a2v ? row0 + 128 : 0) + c * 8;
;   const bf16_t* pa3 = arow(a3v ? row0 + 192 : 0) + c * 8;
;   const bf16_t* pb0 = brow(b0v ? row0 : 0) + c * 8;
;   const bf16_t* pb1 = brow(b1v ? row0 + 64 : 0) + c * 8;
;   const bf16_t* pb2 = brow(b2v ? row0 + 128 : 0) + c * 8;
;   const bf16_t* pb3 = brow(b3v ? row0 + 192 : 0) + c * 8;
;   if (!pre) {
;     char* l_ = smem + t * 16; char* m_ = l_ + RA * LDR;
;     if (a0v) GLDS(pa0, l_); if (a1v) GLDS(pa1, l_ + 8192); if (a2v) GLDS(pa2, l_ + 16384); if (a3v) GLDS(pa3, l_ + 24576);
;     if (b0v) GLDS(pb0, m_); if (b1v) GLDS(pb1, m_ + 8192); if (b2v) GLDS(pb2, m_ + 16384); if (b3v) GLDS(pb3, m_ + 24576);
;   }
;   if (NST == 3) {
;     char* l_ = smem + STAGE + t * 16; char* m_ = l_ + RA * LDR;
;     GLDS(pa0 + 64, l_); GLDS(pa1 + 64, l_ + 8192); GLDS(pa2 + 64, l_ + 16384); GLDS(pa3 + 64, l_ + 24576);
;     GLDS(pb0 + 64, m_); GLDS(pb1 + 64, m_ + 8192);
;     asm volatile("s_waitcnt vmcnt(6)" ::: "memory");
;   } else wait_vm0();
;   bar_();
;   const int nk = K >> 6;
;   const int sw = (r >> 1) & 7;
;   const int aoff = (wm * TM * 32 + r) * LDR, boff = RA * LDR + (wn * TN * 32 + r) * LDR;
; DI void phase2(const Params& p, char* smem) {
;     ...
;     f32x16 acc[4][2];
; #pragma unroll
;     for (int a = 0; a < 4; ++a)
; #pragma unroll
;       for (int b = 0; b < 2; ++b) acc[a][b] = zero16();
.LBB0_222:
	v_ashrrev_i32_e32 v2, 6, v1
	v_lshrrev_b32_e32 v4, 31, v1
	v_add_u32_e32 v4, v2, v4
	v_and_b32_e32 v5, 0x3fffe, v4
	v_bfe_u32 v3, v1, 5, 1
	v_sub_u32_e32 v2, v2, v5
	v_lshrrev_b32_e32 v5, 1, v1
	v_bfe_u32 v6, v1, 1, 3
	v_lshlrev_b32_e32 v1, 7, v1
	v_and_b32_e32 v218, 0xf80, v1
	v_lshlrev_b32_e32 v1, 12, v4
	v_and_b32_e32 v219, 0xffffe000, v1
	v_bitop3_b32 v1, v5, v3, 7 bitop3:0x6c
	v_lshlrev_b32_e32 v216, 4, v1
	v_bitop3_b32 v1, v3, v6, 2 bitop3:0x36
	v_lshlrev_b32_e32 v215, 4, v1
	v_bitop3_b32 v1, v3, v6, 4 bitop3:0x36
	v_lshlrev_b32_e32 v214, 4, v1
	v_bitop3_b32 v1, v3, v6, 6 bitop3:0x36
	v_and_b32_e32 v0, 7, v0
	v_lshl_or_b32 v217, v2, 14, v218
	v_lshlrev_b32_e32 v213, 4, v1
	v_lshl_add_u64 v[2:3], s[46:47], 0, v[188:189]
	v_lshlrev_b32_e32 v0, 4, v0
	v_mov_b32_e32 v1, v185
	v_lshl_add_u64 v[2:3], v[2:3], 0, v[0:1]
	v_lshl_add_u64 v[196:197], s[26:27], 0, v[2:3]
	v_lshl_add_u64 v[2:3], s[46:47], 0, v[190:191]
	v_lshl_add_u64 v[2:3], v[2:3], 0, v[0:1]
	v_lshl_add_u64 v[198:199], s[26:27], 0, v[2:3]
	v_lshl_add_u64 v[2:3], s[46:47], 0, v[192:193]
	v_lshl_add_u64 v[2:3], v[2:3], 0, v[0:1]
	v_lshl_add_u64 v[200:201], s[26:27], 0, v[2:3]
	v_lshl_add_u64 v[2:3], s[46:47], 0, v[194:195]
	v_lshl_add_u64 v[2:3], v[2:3], 0, v[0:1]
	v_lshl_add_u64 v[202:203], s[26:27], 0, v[2:3]
	v_lshl_add_u64 v[2:3], s[44:45], 0, v[188:189]
	v_lshl_add_u64 v[2:3], v[2:3], 0, v[0:1]
	v_lshl_add_u64 v[204:205], s[28:29], 0, v[2:3]
	v_lshl_add_u64 v[2:3], s[44:45], 0, v[190:191]
	v_lshl_add_u64 v[2:3], v[2:3], 0, v[0:1]
	v_lshl_add_u64 v[206:207], s[28:29], 0, v[2:3]
	v_lshl_add_u64 v[2:3], s[44:45], 0, v[192:193]
	v_lshl_add_u64 v[2:3], v[2:3], 0, v[0:1]
	v_lshl_add_u64 v[208:209], s[28:29], 0, v[2:3]
	v_lshl_add_u64 v[2:3], s[44:45], 0, v[194:195]
	s_waitcnt vmcnt(0)
	v_lshl_add_u64 v[0:1], v[2:3], 0, v[0:1]
	v_lshl_add_u64 v[210:211], s[28:29], 0, v[0:1]
	v_mov_b32_e32 v0, 0
	v_or_b32_e32 v222, v218, v219
	s_mov_b32 s13, 0
	s_mov_b64 s[44:45], 0
	v_mov_b32_e32 v1, v0
	v_mov_b32_e32 v2, v0
	v_mov_b32_e32 v3, v0
	v_mov_b32_e32 v4, v0
	v_mov_b32_e32 v5, v0
	v_mov_b32_e32 v6, v0
	v_mov_b32_e32 v7, v0
	v_mov_b32_e32 v8, v0
	v_mov_b32_e32 v9, v0
	v_mov_b32_e32 v10, v0
	v_mov_b32_e32 v11, v0
	v_mov_b32_e32 v12, v0
	v_mov_b32_e32 v13, v0
	v_mov_b32_e32 v14, v0
	v_mov_b32_e32 v15, v0
	v_mov_b32_e32 v64, v0
	v_mov_b32_e32 v65, v0
	v_mov_b32_e32 v66, v0
	v_mov_b32_e32 v67, v0
	v_mov_b32_e32 v68, v0
	v_mov_b32_e32 v69, v0
	v_mov_b32_e32 v70, v0
	v_mov_b32_e32 v71, v0
	v_mov_b32_e32 v72, v0
	v_mov_b32_e32 v73, v0
	v_mov_b32_e32 v74, v0
	v_mov_b32_e32 v75, v0
	v_mov_b32_e32 v76, v0
	v_mov_b32_e32 v77, v0
	v_mov_b32_e32 v78, v0
	v_mov_b32_e32 v79, v0
	v_mov_b32_e32 v16, v0
	v_mov_b32_e32 v17, v0
	v_mov_b32_e32 v18, v0
	v_mov_b32_e32 v19, v0
	v_mov_b32_e32 v20, v0
	v_mov_b32_e32 v21, v0
	v_mov_b32_e32 v22, v0
	v_mov_b32_e32 v23, v0
	v_mov_b32_e32 v24, v0
	v_mov_b32_e32 v25, v0
	v_mov_b32_e32 v26, v0
	v_mov_b32_e32 v27, v0
	v_mov_b32_e32 v28, v0
	v_mov_b32_e32 v29, v0
	v_mov_b32_e32 v30, v0
	v_mov_b32_e32 v31, v0
	v_mov_b32_e32 v80, v0
	v_mov_b32_e32 v81, v0
	v_mov_b32_e32 v82, v0
	v_mov_b32_e32 v83, v0
	v_mov_b32_e32 v84, v0
	v_mov_b32_e32 v85, v0
	v_mov_b32_e32 v86, v0
	v_mov_b32_e32 v87, v0
	v_mov_b32_e32 v88, v0
	v_mov_b32_e32 v89, v0
	v_mov_b32_e32 v90, v0
	v_mov_b32_e32 v91, v0
	v_mov_b32_e32 v92, v0
	v_mov_b32_e32 v93, v0
	v_mov_b32_e32 v94, v0
	v_mov_b32_e32 v95, v0
	v_mov_b32_e32 v32, v0
	v_mov_b32_e32 v33, v0
	v_mov_b32_e32 v34, v0
	v_mov_b32_e32 v35, v0
	v_mov_b32_e32 v36, v0
	v_mov_b32_e32 v37, v0
	v_mov_b32_e32 v38, v0
	v_mov_b32_e32 v39, v0
	v_mov_b32_e32 v40, v0
	v_mov_b32_e32 v41, v0
	v_mov_b32_e32 v42, v0
	v_mov_b32_e32 v43, v0
	v_mov_b32_e32 v44, v0
	v_mov_b32_e32 v45, v0
	v_mov_b32_e32 v46, v0
	v_mov_b32_e32 v47, v0
	v_mov_b32_e32 v96, v0
	v_mov_b32_e32 v97, v0
	v_mov_b32_e32 v98, v0
	v_mov_b32_e32 v99, v0
	v_mov_b32_e32 v100, v0
	v_mov_b32_e32 v101, v0
	v_mov_b32_e32 v102, v0
	v_mov_b32_e32 v103, v0
	v_mov_b32_e32 v104, v0
	v_mov_b32_e32 v105, v0
	v_mov_b32_e32 v106, v0
	v_mov_b32_e32 v107, v0
	v_mov_b32_e32 v108, v0
	v_mov_b32_e32 v109, v0
	v_mov_b32_e32 v110, v0
	v_mov_b32_e32 v111, v0
	v_mov_b32_e32 v48, v0
	v_mov_b32_e32 v49, v0
	v_mov_b32_e32 v50, v0
	v_mov_b32_e32 v51, v0
	v_mov_b32_e32 v52, v0
	v_mov_b32_e32 v53, v0
	v_mov_b32_e32 v54, v0
	v_mov_b32_e32 v55, v0
	v_mov_b32_e32 v56, v0
	v_mov_b32_e32 v57, v0
	v_mov_b32_e32 v58, v0
	v_mov_b32_e32 v59, v0
	v_mov_b32_e32 v60, v0
	v_mov_b32_e32 v61, v0
	v_mov_b32_e32 v62, v0
	v_mov_b32_e32 v63, v0
	v_mov_b32_e32 v112, v0
	v_mov_b32_e32 v113, v0
	v_mov_b32_e32 v114, v0
	v_mov_b32_e32 v115, v0
	v_mov_b32_e32 v116, v0
	v_mov_b32_e32 v117, v0
	v_mov_b32_e32 v118, v0
	v_mov_b32_e32 v119, v0
	v_mov_b32_e32 v120, v0
	v_mov_b32_e32 v121, v0
	v_mov_b32_e32 v122, v0
	v_mov_b32_e32 v123, v0
	v_mov_b32_e32 v124, v0
	v_mov_b32_e32 v125, v0
	v_mov_b32_e32 v126, v0
	v_mov_b32_e32 v127, v0
	s_barrier
	v_readfirstlane_b32 s66, v212
; DI void wait_vm0() { asm volatile("s_waitcnt vmcnt(0)" ::: "memory"); }
; DI void bar_() { __builtin_amdgcn_s_barrier(); }
; #define GLDS(gp, lp) __builtin_amdgcn_global_load_lds((const unsigned*)(gp), (__attribute__((address_space(3))) unsigned*)(lp), 16, 0, 0)
; #define SB_ __builtin_amdgcn_sched_barrier(0)
; #define LOADF(A_, B_, ks) do { const int po_ = (((ks) * 2 + hh) ^ sw) * 16; \
;       _Pragma("unroll") for (int tm = 0; tm < TM; ++tm) A_[tm] = *(const bf16x8*)(As + tm * 32 * LDR + po_); \
;       _Pragma("unroll") for (int tn = 0; tn < TN; ++tn) B_[tn] = *(const bf16x8*)(Bs + tn * 32 * LDR + po_); } while (0)
; template <int TM, int TN, int WM, int WN, bool SUMSQ, int NST, class AF, class BF, class AFN, class BFN>
; DI void gemm8x(f32x16 (&acc)[TM][TN], AF arow, BF brow, int K, char* smem, float& sumsq, bool pre, bool hasNext, AFN arowN, BFN browN) {
;     ...
;   auto compute = [&](const char* cur, char* nxt, bool issue, const bf16_t* q0, const bf16_t* q1, const bf16_t* q2, const bf16_t* q3,
;                      const bf16_t* s0, const bf16_t* s1, const bf16_t* s2, const bf16_t* s3) {
;     const char* As = cur + aoff;
;     const char* Bs = cur + boff;
;     char* l_ = nxt + t * 16; char* m_ = l_ + RA * LDR;
;     bf16x8 a0[TM], b0[TN], a1[TM], b1[TN];
;     ...
;     LOADF(a0, b0, 0);
;     LOADF(a1, b1, 1);
;     SB_;
;     if (issue) { if (a0v) GLDS(q0, l_); if (a1v) GLDS(q1, l_ + 8192); }
;     SB_;
;     __builtin_amdgcn_s_setprio(1);
;     MMF(a0, b0);
;     LOADF(a0, b0, 2);
;     SB_;
;     if (issue) { if (a2v) GLDS(q2, l_ + 16384); if (a3v) GLDS(q3, l_ + 24576); }
;     SB_;
;     MMF(a1, b1);
;     LOADF(a1, b1, 3);
;     SB_;
;     if (issue) { if (b0v) GLDS(s0, m_); if (b1v) GLDS(s1, m_ + 8192); }
;     SB_;
;     MMF(a0, b0);
;     SB_;
;     if (issue) { if (b2v) GLDS(s2, m_ + 16384); if (b3v) GLDS(s3, m_ + 24576); }
;     SB_;
;     MMF(a1, b1);
;     __builtin_amdgcn_s_setprio(0);
;   };
;   int sc_ = 0;
;   for (int kt = 0; kt < nk - 1; ++kt) {
;     SB_;
;     if (NST == 2) {
;       const int ko = (kt + 1) * 64;
;       compute(smem + (kt & 1) * STAGE, smem + ((kt + 1) & 1) * STAGE, true, pa0 + ko, pa1 + ko, pa2 + ko, pa3 + ko, pb0 + ko, pb1 + ko, pb2 + ko, pb3 + ko);
;       SB_;
;       wait_vm0(); bar_();
.LBB0_224:
	s_and_b32 s37, s13, 0x10000
	v_add_u32_e32 v225, s37, v222
	v_add_u32_e32 v224, s37, v217
	v_add_u32_e32 v226, v225, v216
	v_add_u32_e32 v128, v224, v216
	ds_read_b128 v[164:167], v226 offset:32768
	ds_read_b128 v[172:175], v128
	ds_read_b128 v[156:159], v226 offset:36864
	ds_read_b128 v[168:171], v128 offset:4096
	ds_read_b128 v[160:163], v128 offset:8192
	ds_read_b128 v[152:155], v128 offset:12288
	v_add_u32_e32 v227, v225, v215
	v_add_u32_e32 v128, v224, v215
	ds_read_b128 v[140:143], v227 offset:32768
	ds_read_b128 v[148:151], v128
	ds_read_b128 v[132:135], v227 offset:36864
	ds_read_b128 v[144:147], v128 offset:4096
	ds_read_b128 v[136:139], v128 offset:8192
	ds_read_b128 v[128:131], v128 offset:12288
	s_add_i32 s13, s13, 0x10000
	s_and_b32 s37, s13, 0x10000
	s_add_i32 s37, s37, s66
	v_lshl_add_u64 v[228:229], v[196:197], 0, s[44:45]
	s_mov_b32 m0, s37
	s_setprio 1
	s_waitcnt lgkmcnt(10)
	v_mfma_f32_32x32x16_bf16 v[112:127], v[172:175], v[164:167], v[112:127]
	global_load_lds_dwordx4 v[228:229], off
	v_lshl_add_u64 v[230:231], v[198:199], 0, s[44:45]
	s_waitcnt lgkmcnt(9)
	v_mfma_f32_32x32x16_bf16 v[48:63], v[172:175], v[156:159], v[48:63]
	s_add_u32 m0, s37, 0x2000
	s_waitcnt lgkmcnt(8)
	v_mfma_f32_32x32x16_bf16 v[96:111], v[168:171], v[164:167], v[96:111]
	global_load_lds_dwordx4 v[230:231], off
	v_lshl_add_u64 v[228:229], v[200:201], 0, s[44:45]
	v_mfma_f32_32x32x16_bf16 v[32:47], v[168:171], v[156:159], v[32:47]
	s_add_u32 m0, s37, 0x4000
	s_waitcnt lgkmcnt(7)
	v_mfma_f32_32x32x16_bf16 v[80:95], v[160:163], v[164:167], v[80:95]
	global_load_lds_dwordx4 v[228:229], off
	v_lshl_add_u64 v[230:231], v[202:203], 0, s[44:45]
	v_mfma_f32_32x32x16_bf16 v[16:31], v[160:163], v[156:159], v[16:31]
	s_add_u32 m0, s37, 0x6000
	v_add_u32_e32 v226, v224, v214
	v_add_u32_e32 v227, v225, v214
	s_waitcnt lgkmcnt(6)
	v_mfma_f32_32x32x16_bf16 v[64:79], v[152:155], v[164:167], v[64:79]
	global_load_lds_dwordx4 v[230:231], off
	ds_read_b128 v[180:183], v226
	ds_read_b128 v[176:179], v226 offset:4096
	ds_read_b128 v[164:167], v226 offset:8192
	ds_read_b128 v[160:163], v226 offset:12288
	ds_read_b128 v[172:175], v227 offset:32768
	ds_read_b128 v[168:171], v227 offset:36864
	v_mfma_f32_32x32x16_bf16 v[0:15], v[152:155], v[156:159], v[0:15]
	v_lshl_add_u64 v[228:229], v[204:205], 0, s[44:45]
	s_add_u32 m0, s37, 0x8000
	s_waitcnt lgkmcnt(6)
	v_mfma_f32_32x32x16_bf16 v[112:127], v[148:151], v[140:143], v[112:127]
	global_load_lds_dwordx4 v[228:229], off
	v_lshl_add_u64 v[230:231], v[206:207], 0, s[44:45]
	v_mfma_f32_32x32x16_bf16 v[48:63], v[148:151], v[132:135], v[48:63]
	s_add_u32 m0, s37, 0xa000
	v_mfma_f32_32x32x16_bf16 v[96:111], v[144:147], v[140:143], v[96:111]
	global_load_lds_dwordx4 v[230:231], off
	v_lshl_add_u64 v[228:229], v[208:209], 0, s[44:45]
	v_mfma_f32_32x32x16_bf16 v[32:47], v[144:147], v[132:135], v[32:47]
	s_add_u32 m0, s37, 0xc000
	v_mfma_f32_32x32x16_bf16 v[80:95], v[136:139], v[140:143], v[80:95]
	global_load_lds_dwordx4 v[228:229], off
	v_lshl_add_u64 v[230:231], v[210:211], 0, s[44:45]
	v_mfma_f32_32x32x16_bf16 v[16:31], v[136:139], v[132:135], v[16:31]
	s_add_u32 m0, s37, 0xe000
	v_add_u32_e32 v226, v224, v213
	v_add_u32_e32 v227, v225, v213
	v_mfma_f32_32x32x16_bf16 v[64:79], v[128:131], v[140:143], v[64:79]
	global_load_lds_dwordx4 v[230:231], off
	ds_read_b128 v[156:159], v226
	ds_read_b128 v[152:155], v226 offset:4096
	ds_read_b128 v[140:143], v226 offset:8192
	ds_read_b128 v[136:139], v226 offset:12288
	ds_read_b128 v[148:151], v227 offset:32768
	ds_read_b128 v[144:147], v227 offset:36864
	v_mfma_f32_32x32x16_bf16 v[0:15], v[128:131], v[132:135], v[0:15]
	s_waitcnt lgkmcnt(6)
	v_mfma_f32_32x32x16_bf16 v[112:127], v[180:183], v[172:175], v[112:127]
	v_mfma_f32_32x32x16_bf16 v[48:63], v[180:183], v[168:171], v[48:63]
	v_mfma_f32_32x32x16_bf16 v[96:111], v[176:179], v[172:175], v[96:111]
	v_mfma_f32_32x32x16_bf16 v[32:47], v[176:179], v[168:171], v[32:47]
	v_mfma_f32_32x32x16_bf16 v[80:95], v[164:167], v[172:175], v[80:95]
	v_mfma_f32_32x32x16_bf16 v[16:31], v[164:167], v[168:171], v[16:31]
	v_mfma_f32_32x32x16_bf16 v[64:79], v[160:163], v[172:175], v[64:79]
	v_mfma_f32_32x32x16_bf16 v[0:15], v[160:163], v[168:171], v[0:15]
	s_waitcnt lgkmcnt(0)
	v_mfma_f32_32x32x16_bf16 v[112:127], v[156:159], v[148:151], v[112:127]
	v_mfma_f32_32x32x16_bf16 v[48:63], v[156:159], v[144:147], v[48:63]
	v_mfma_f32_32x32x16_bf16 v[96:111], v[152:155], v[148:151], v[96:111]
	v_mfma_f32_32x32x16_bf16 v[32:47], v[152:155], v[144:147], v[32:47]
	v_mfma_f32_32x32x16_bf16 v[80:95], v[140:143], v[148:151], v[80:95]
	v_mfma_f32_32x32x16_bf16 v[16:31], v[140:143], v[144:147], v[16:31]
	v_mfma_f32_32x32x16_bf16 v[64:79], v[136:139], v[148:151], v[64:79]
	v_mfma_f32_32x32x16_bf16 v[0:15], v[136:139], v[144:147], v[0:15]
	s_setprio 0
	s_waitcnt vmcnt(0)
	s_add_u32 s44, s44, 0x80
	s_addc_u32 s45, s45, 0
	s_cmpk_eq_i32 s44, 0x780
	s_barrier
	s_cbranch_scc0 .LBB0_224
